# gla_scan: o tile computed transposed, one dwordx2 store per lane instead of 4 short stores
# baseline (speedup 1.0000x reference)
; #define LAS __attribute__((address_space(3)))
; DI bf16_t f2bf(float f) { return (bf16_t)(pk2(f, 0.f) & 0xffffu); }
; DI void gla_scan(const Params& P, LAS unsigned char* lds) {
;     ...
;             if (tid < 256) { const int s = tid & 63, v8 = (tid >> 6) * 8; const bf16_t* e = (const bf16_t*)&vw;
; #pragma unroll
;                 for (int j = 0; j < 8; ++j) Vt[(v8 + j) * 72 + s] = e[j]; }
; #pragma unroll
;             for (int i = 0; i < 2; ++i) { const int idx = tid + 512 * i, s = idx & 63, d8 = (idx >> 6) * 8; const bf16_t* e = (const bf16_t*)&kw[i];
; #pragma unroll
;                 for (int j = 0; j < 8; ++j) KIt[(d8 + j) * 72 + s] = e[j]; }
; #pragma unroll
;             for (int i = 0; i < 2; ++i) { const int nb = 2 * vb + i; f32x4 sc = {0.f, 0.f, 0.f, 0.f};
; #pragma unroll
;                 for (int ks = 0; ks < 4; ++ks) sc = MFMA16(qa[ks], kbf[i][ks], sc);
; #pragma unroll
;                 for (int j = 0; j < 4; ++j) { const int t = 16 * mb + 4 * fq + j, s = 16 * nb + fr; Pm[t * 72 + s] = f2bf(s <= t ? sc[j] : 0.f); } }
;             LDS_BARRIER();
;             bf16x8 qn[4]; f32x4 dn = dc;
; #pragma unroll
;             for (int ks = 0; ks < 4; ++ks) qn[ks] = qa[ks];
;             if (n + 1 < 32) GLA_LOAD(row0 + 64, b * 32 + n + 1, qn, dn);
;             f32x4 o = {0.f, 0.f, 0.f, 0.f};
; #pragma unroll
;             for (int k2 = 0; k2 < 2; ++k2) { const bf16x8 a = *(const LAS bf16x8*)(Pm + (16 * mb + fr) * 72 + 32 * k2 + 8 * fq); const bf16x8 bb = *(const LAS bf16x8*)(Vt + (16 * vb + fr) * 72 + 32 * k2 + 8 * fq); o = MFMA16(a, bb, o); }
; #pragma unroll
;             for (int ks = 0; ks < 4; ++ks) { const bf16x8 bb = *(const LAS bf16x8*)(St + (16 * vb + fr) * 136 + 32 * ks + 8 * fq); o = MFMA16(qa[ks], bb, o); }
; #pragma unroll
;             for (int j = 0; j < 4; ++j) { const int row = row0 + 16 * mb + 4 * fq + j; OB[(size_t)row * DM + h * 256 + vs * 32 + 16 * vb + fr] = f2bf(o[j]); }
; #pragma unroll
;             for (int k2 = 0; k2 < 2; ++k2) { const bf16x8 a = *(const LAS bf16x8*)(KIt + (16 * wid + fr) * 72 + 32 * k2 + 8 * fq);
; #pragma unroll
;                 for (int v2 = 0; v2 < 2; ++v2) { const bf16x8 bb = *(const LAS bf16x8*)(Vt + (16 * v2 + fr) * 72 + 32 * k2 + 8 * fq); Sacc[v2] = MFMA16(a, bb, Sacc[v2]); } }
;             Sacc[0] *= dc; Sacc[1] *= dc;
; #pragma unroll
.LBB0_1074:
	s_or_b64 exec, exec, s[16:17]
	v_add_u32_e32 v16, v144, v140
	s_waitcnt vmcnt(15)
	ds_write_b16 v16, v74 offset:63488
	ds_write_b16_d16_hi v16, v74 offset:63632
	ds_write_b16 v16, v75 offset:63776
	ds_write_b16_d16_hi v16, v75 offset:63920
	ds_write_b16 v16, v76 offset:64064
	ds_write_b16_d16_hi v16, v76 offset:64208
	ds_write_b16 v16, v77 offset:64352
	ds_write_b16_d16_hi v16, v77 offset:64496
	s_waitcnt vmcnt(14)
	ds_write_b16 v151, v70 offset:63488
	ds_write_b16_d16_hi v152, v70 offset:63488
	ds_write_b16 v153, v71 offset:63488
	ds_write_b16_d16_hi v154, v71 offset:63488
	ds_write_b16 v155, v72 offset:63488
	ds_write_b16_d16_hi v156, v72 offset:63488
	ds_write_b16 v157, v73 offset:63488
	ds_write_b16_d16_hi v158, v73 offset:63488
	s_waitcnt vmcnt(1)
	v_mfma_f32_16x16x32_bf16 v[16:19], v[66:69], v[50:53], 0
	s_lshl_b32 s15, s21, 2
	s_or_b32 s18, s15, s20
	s_ashr_i32 s19, s18, 31
	v_mfma_f32_16x16x32_bf16 v[16:19], v[58:61], v[46:49], v[16:19]
	s_lshl_b64 s[18:19], s[18:19], 17
	v_mfma_f32_16x16x32_bf16 v[16:19], v[78:81], v[38:41], v[16:19]
	v_mfma_f32_16x16x32_bf16 v[16:19], v[62:65], v[30:33], v[16:19]
	s_nop 7
	v_cvt_pk_bf16_f32 v16, v16, s0
	v_cndmask_b32_e64 v16, v16, 0, s[40:41]
	ds_write_b16 v159, v16 offset:40960
	v_cvt_pk_bf16_f32 v16, v17, s0
	v_cndmask_b32_e64 v16, v16, 0, s[42:43]
	ds_write_b16 v159, v16 offset:41104
	v_cvt_pk_bf16_f32 v16, v18, s0
	v_cndmask_b32_e64 v16, v16, 0, s[44:45]
	ds_write_b16 v159, v16 offset:41248
	v_cvt_pk_bf16_f32 v16, v19, s0
	v_cndmask_b32_e64 v16, v16, 0, s[46:47]
	ds_write_b16 v159, v16 offset:41392
	v_mfma_f32_16x16x32_bf16 v[16:19], v[66:69], v[26:29], 0
	v_mfma_f32_16x16x32_bf16 v[16:19], v[58:61], v[20:23], v[16:19]
	v_mfma_f32_16x16x32_bf16 v[12:15], v[78:81], v[12:15], v[16:19]
	v_mfma_f32_16x16x32_bf16 v[8:11], v[62:65], v[8:11], v[12:15]
	s_nop 7
	v_cvt_pk_bf16_f32 v8, v8, s0
	v_cndmask_b32_e64 v8, v8, 0, s[48:49]
	ds_write_b16 v159, v8 offset:40992
	v_cvt_pk_bf16_f32 v8, v9, s0
	v_cndmask_b32_e64 v8, v8, 0, s[50:51]
	ds_write_b16 v159, v8 offset:41136
	v_cvt_pk_bf16_f32 v8, v10, s0
	v_cndmask_b32_e64 v8, v8, 0, s[52:53]
	ds_write_b16 v159, v8 offset:41280
	v_cvt_pk_bf16_f32 v8, v11, s0
	v_cndmask_b32_e64 v8, v8, 0, s[54:55]
	ds_write_b16 v159, v8 offset:41424
	s_waitcnt lgkmcnt(0)
	s_barrier
	ds_read_b128 v[8:11], v137 offset:40960
	ds_read_b128 v[12:15], v138 offset:50176
	s_waitcnt lgkmcnt(0)
	v_mfma_f32_16x16x32_bf16 v[8:11], v[12:15], v[8:11], 0
	ds_read_b128 v[12:15], v137 offset:41024
	ds_read_b128 v[16:19], v138 offset:50240
	s_waitcnt lgkmcnt(0)
	v_mfma_f32_16x16x32_bf16 v[8:11], v[16:19], v[12:15], v[8:11]
	ds_read_b128 v[12:15], v160 offset:54784
	v_add_u32_e32 v16, v136, v142
	s_waitcnt lgkmcnt(0)
	v_mfma_f32_16x16x32_bf16 v[8:11], v[12:15], v[66:69], v[8:11]
	ds_read_b128 v[12:15], v160 offset:54848
	s_waitcnt lgkmcnt(0)
	v_mfma_f32_16x16x32_bf16 v[8:11], v[12:15], v[58:61], v[8:11]
	ds_read_b128 v[12:15], v160 offset:54912
	s_waitcnt lgkmcnt(0)
	v_mfma_f32_16x16x32_bf16 v[8:11], v[12:15], v[78:81], v[8:11]
	ds_read_b128 v[12:15], v160 offset:54976
	s_waitcnt lgkmcnt(0)
	v_mfma_f32_16x16x32_bf16 v[8:11], v[12:15], v[62:65], v[8:11]
	v_and_b32_e32 v12, 15, v187
	v_lshrrev_b32_e32 v13, 4, v187
	v_lshlrev_b32_e32 v14, 2, v13
	v_sub_u32_e32 v14, v12, v14
	v_add_u32_e32 v14, v14, v24
	v_add_u32_e32 v14, 0x7c0, v14
	v_ashrrev_i32_e32 v15, 31, v14
	v_lshlrev_b64 v[14:15], 11, v[14:15]
	v_lshlrev_b32_e32 v13, 3, v13
	v_lshlrev_b32_e32 v12, 1, v12
	v_sub_u32_e32 v12, v13, v12
	v_ashrrev_i32_e32 v13, 31, v12
	v_lshl_add_u64 v[14:15], v[116:117], 0, v[14:15]
	v_lshl_add_u64 v[14:15], v[14:15], 0, v[12:13]
	v_cvt_pk_bf16_f32 v8, v8, v9
	v_cvt_pk_bf16_f32 v9, v10, v11
	global_store_dwordx2 v[14:15], v[8:9], off
	ds_read_b128 v[8:11], v145 offset:63488
	ds_read_b128 v[12:15], v16 offset:50176
	s_waitcnt lgkmcnt(0)
	v_mfma_f32_16x16x32_bf16 v[0:3], v[8:11], v[12:15], v[0:3]
	ds_read_b128 v[12:15], v16 offset:52480
	v_lshlrev_b32_e32 v24, 2, v82
	s_waitcnt lgkmcnt(0)
	v_mfma_f32_16x16x32_bf16 v[4:7], v[8:11], v[12:15], v[4:7]
	ds_read_b128 v[8:11], v145 offset:63552
	ds_read_b128 v[12:15], v16 offset:50240
	s_load_dwordx2 s[16:17], s[0:1], 0x150
	s_waitcnt lgkmcnt(0)
	s_add_u32 s16, s16, s18
	v_mfma_f32_16x16x32_bf16 v[0:3], v[8:11], v[12:15], v[0:3]
	ds_read_b128 v[12:15], v16 offset:52544
	s_addc_u32 s17, s17, s19
	s_waitcnt lgkmcnt(0)
	v_mfma_f32_16x16x32_bf16 v[4:7], v[8:11], v[12:15], v[4:7]
	v_add_u32_e32 v10, v146, v143
	s_nop 2
	v_pk_mul_f32 v[2:3], v[36:37], v[2:3]
	v_pk_mul_f32 v[0:1], v[34:35], v[0:1]
	s_nop 1
	v_pk_mul_f32 v[6:7], v[36:37], v[6:7]
	v_pk_mul_f32 v[4:5], v[34:35], v[4:5]
	v_cvt_pk_bf16_f32 v8, v0, v1
	v_cvt_pk_bf16_f32 v9, v2, v3
	ds_write_b64 v10, v[8:9] offset:13824
	v_cvt_pk_bf16_f32 v8, v4, v5
	v_cvt_pk_bf16_f32 v9, v6, v7
	ds_write_b64 v10, v[8:9] offset:18176
	v_lshl_add_u64 v[8:9], v[114:115], 2, s[16:17]
	v_lshl_add_u64 v[8:9], v[8:9], 0, v[24:25]
	s_mov_b64 s[16:17], 0x4bf8000
	v_lshl_add_u64 v[8:9], v[8:9], 0, s[16:17]
	v_lshl_add_u64 v[10:11], v[8:9], 0, v[92:93]
	v_lshl_add_u64 v[12:13], v[8:9], 0, v[94:95]
	global_store_dword v[10:11], v0, off
	global_store_dword v[12:13], v1, off
	v_lshl_add_u64 v[0:1], v[8:9], 0, v[96:97]
	v_lshl_add_u64 v[8:9], v[8:9], 0, v[98:99]
	global_store_dword v[0:1], v2, off
	global_store_dword v[8:9], v3, off
	global_store_dword v[10:11], v4, off offset:64
	global_store_dword v[12:13], v5, off offset:64
	global_store_dword v[0:1], v6, off offset:64
	global_store_dword v[8:9], v7, off offset:64
	v_readlane_b32 s16, v255, 13
	s_waitcnt lgkmcnt(0)
	s_barrier
	v_readlane_b32 s17, v255, 14
	s_load_dword s15, s[16:17], 0x0
	s_waitcnt lgkmcnt(0)
	s_add_i32 s22, s15, s22
	s_cmpk_gt_i32 s22, 0xff
	s_cbranch_scc1 .LBB0_1094

; DI bf16_t f2bf(float f) { return (bf16_t)(pk2(f, 0.f) & 0xffffu); }
; #define MFMA16(a, b, c) __builtin_amdgcn_mfma_f32_16x16x32_bf16((a), (b), (c), 0, 0, 0)
; DI void gla_scan(const Params& P, LAS unsigned char* lds) {
;     ...
;             if (tid < 256) { const int s = tid & 63, v8 = (tid >> 6) * 8; const bf16_t* e = (const bf16_t*)&vw;
; #pragma unroll
;                 for (int j = 0; j < 8; ++j) Vt[(v8 + j) * 72 + s] = e[j]; }
; #pragma unroll
;             for (int i = 0; i < 2; ++i) { const int idx = tid + 512 * i, s = idx & 63, d8 = (idx >> 6) * 8; const bf16_t* e = (const bf16_t*)&kw[i];
; #pragma unroll
;                 for (int j = 0; j < 8; ++j) KIt[(d8 + j) * 72 + s] = e[j]; }
; #pragma unroll
;             for (int i = 0; i < 2; ++i) { const int nb = 2 * vb + i; f32x4 sc = {0.f, 0.f, 0.f, 0.f};
; #pragma unroll
;                 for (int ks = 0; ks < 4; ++ks) sc = MFMA16(qa[ks], kbf[i][ks], sc);
; #pragma unroll
;                 for (int j = 0; j < 4; ++j) { const int t = 16 * mb + 4 * fq + j, s = 16 * nb + fr; Pm[t * 72 + s] = f2bf(s <= t ? sc[j] : 0.f); } }
.LBB0_1088:
	s_or_b64 exec, exec, s[16:17]
	v_add3_u32 v34, s29, v34, v140
	s_waitcnt vmcnt(14)
	ds_write_b16 v34, v74 offset:22528
	ds_write_b16_d16_hi v34, v74 offset:22672
	ds_write_b16 v34, v75 offset:22816
	ds_write_b16_d16_hi v34, v75 offset:22960
	ds_write_b16 v34, v76 offset:23104
	ds_write_b16_d16_hi v34, v76 offset:23248
	ds_write_b16 v34, v77 offset:23392
	ds_write_b16_d16_hi v34, v77 offset:23536
	s_waitcnt vmcnt(13)
	ds_write_b16 v34, v70 offset:31744
	ds_write_b16_d16_hi v34, v70 offset:31888
	ds_write_b16 v34, v71 offset:32032
	ds_write_b16_d16_hi v34, v71 offset:32176
	ds_write_b16 v34, v72 offset:32320
	ds_write_b16_d16_hi v34, v72 offset:32464
	ds_write_b16 v34, v73 offset:32608
	ds_write_b16_d16_hi v34, v73 offset:32752
	s_waitcnt vmcnt(1)
	v_mfma_f32_16x16x32_bf16 v[34:37], v[66:69], v[50:53], 0
	s_waitcnt vmcnt(4)
	v_mfma_f32_16x16x32_bf16 v[26:29], v[66:69], v[26:29], 0
	v_mfma_f32_16x16x32_bf16 v[34:37], v[62:65], v[46:49], v[34:37]
	s_waitcnt vmcnt(3)
	v_mfma_f32_16x16x32_bf16 v[20:23], v[62:65], v[20:23], v[26:29]
	v_mfma_f32_16x16x32_bf16 v[34:37], v[58:61], v[38:41], v[34:37]
	s_waitcnt vmcnt(2)
	v_mfma_f32_16x16x32_bf16 v[12:15], v[58:61], v[12:15], v[20:23]
	v_mfma_f32_16x16x32_bf16 v[30:33], v[54:57], v[30:33], v[34:37]
	s_waitcnt vmcnt(1)
	v_mfma_f32_16x16x32_bf16 v[8:11], v[54:57], v[8:11], v[12:15]
	s_nop 2
	v_lshlrev_b32_e32 v34, 1, v131
	s_nop 1
	v_cvt_pk_bf16_f32 v30, v30, s0
	v_cndmask_b32_e64 v30, v30, 0, s[40:41]
	v_add3_u32 v34, s29, v34, v141
	ds_write_b16 v34, v30
	v_cvt_pk_bf16_f32 v8, v8, s0
	v_cndmask_b32_e64 v8, v8, 0, s[48:49]
	v_cvt_pk_bf16_f32 v30, v31, s0
	ds_write_b16 v34, v8 offset:32
	v_cvt_pk_bf16_f32 v8, v9, s0
	v_cndmask_b32_e64 v30, v30, 0, s[42:43]
	v_cndmask_b32_e64 v8, v8, 0, s[50:51]
	ds_write_b16 v34, v30 offset:144
	v_cvt_pk_bf16_f32 v30, v32, s0
	ds_write_b16 v34, v8 offset:176
	v_cvt_pk_bf16_f32 v8, v10, s0
	v_cndmask_b32_e64 v30, v30, 0, s[44:45]
	v_cndmask_b32_e64 v8, v8, 0, s[52:53]
	ds_write_b16 v34, v30 offset:288
	v_cvt_pk_bf16_f32 v30, v33, s0
	ds_write_b16 v34, v8 offset:320
	v_cvt_pk_bf16_f32 v8, v11, s0
	v_cndmask_b32_e64 v30, v30, 0, s[46:47]
	v_cndmask_b32_e64 v8, v8, 0, s[54:55]
	ds_write_b16 v34, v30 offset:432
	ds_write_b16 v34, v8 offset:464
	s_waitcnt lgkmcnt(0)
	s_barrier
	v_add_u32_e32 v8, s15, v111
	v_ashrrev_i32_e32 v9, 31, v8
	s_and_saveexec_b64 s[16:17], vcc
	s_cbranch_execz .LBB0_1090
	v_mad_i64_i32 v[10:11], s[56:57], v8, s87, v[122:123]
	global_load_dwordx4 v[16:19], v[10:11], off offset:2048
; #define LAS __attribute__((address_space(3)))
; DI void gla_scan(const Params& P, LAS unsigned char* lds) {
;     ...
;         GLA_LOAD(b * 2048, b * 32, qa, dc);
;         for (int n = 0; n < 32; ++n) {
;             const int row0 = b * 2048 + 64 * n;
;             LAS unsigned char* sb_ = lds + (n & 1) * GSET; LAS unsigned char* so_ = lds + ((n & 1) ^ 1) * GSET;
;             LAS bf16_t* Pm = (LAS bf16_t*)sb_; LAS bf16_t* Vt = (LAS bf16_t*)(sb_ + 9216); LAS bf16_t* St = (LAS bf16_t*)(sb_ + 13824); LAS bf16_t* KIt = (LAS bf16_t*)(sb_ + 22528);
;             LAS bf16_t* Stn = (LAS bf16_t*)(so_ + 13824);
;             if (tid < 256) { const int s = tid & 63, v8 = (tid >> 6) * 8; const bf16_t* e = (const bf16_t*)&vw;
; #pragma unroll
;                 for (int j = 0; j < 8; ++j) Vt[(v8 + j) * 72 + s] = e[j]; }
; #pragma unroll
;             for (int i = 0; i < 2; ++i) { const int idx = tid + 512 * i, s = idx & 63, d8 = (idx >> 6) * 8; const bf16_t* e = (const bf16_t*)&kw[i];
; #pragma unroll
;                 for (int j = 0; j < 8; ++j) KIt[(d8 + j) * 72 + s] = e[j]; }
; #pragma unroll
;             for (int i = 0; i < 2; ++i) { const int nb = 2 * vb + i; f32x4 sc = {0.f, 0.f, 0.f, 0.f};
; #pragma unroll
;                 for (int ks = 0; ks < 4; ++ks) sc = MFMA16(qa[ks], kbf[i][ks], sc);
; #pragma unroll
;                 for (int j = 0; j < 4; ++j) { const int t = 16 * mb + 4 * fq + j, s = 16 * nb + fr; Pm[t * 72 + s] = f2bf(s <= t ? sc[j] : 0.f); } }
;             LDS_BARRIER();
;             bf16x8 qn[4]; f32x4 dn = dc;
; #pragma unroll
;             for (int ks = 0; ks < 4; ++ks) qn[ks] = qa[ks];
;             if (n + 1 < 32) GLA_LOAD(row0 + 64, b * 32 + n + 1, qn, dn);
;             f32x4 o = {0.f, 0.f, 0.f, 0.f};
; #pragma unroll
;             for (int k2 = 0; k2 < 2; ++k2) { const bf16x8 a = *(const LAS bf16x8*)(Pm + (16 * mb + fr) * 72 + 32 * k2 + 8 * fq); const bf16x8 bb = *(const LAS bf16x8*)(Vt + (16 * vb + fr) * 72 + 32 * k2 + 8 * fq); o = MFMA16(a, bb, o); }
; #pragma unroll
;             for (int ks = 0; ks < 4; ++ks) { const bf16x8 bb = *(const LAS bf16x8*)(St + (16 * vb + fr) * 136 + 32 * ks + 8 * fq); o = MFMA16(qa[ks], bb, o); }
; #pragma unroll
;             for (int j = 0; j < 4; ++j) { const int row = row0 + 16 * mb + 4 * fq + j; OB[(size_t)row * DM + h * 256 + vs * 32 + 16 * vb + fr] = f2bf(o[j]); }
; #pragma unroll
.LBB0_1090:
	s_or_b64 exec, exec, s[16:17]
	v_lshlrev_b64 v[8:9], 10, v[8:9]
	v_lshl_add_u64 v[8:9], v[124:125], 0, v[8:9]
	v_add_u32_e32 v10, s15, v109
	global_load_dwordx4 v[74:77], v[8:9], off
	global_load_dwordx4 v[70:73], v[8:9], off offset:128
	v_add_u32_e32 v8, 64, v10
	v_ashrrev_i32_e32 v9, 31, v8
	v_lshlrev_b64 v[8:9], 10, v[8:9]
	v_lshl_add_u64 v[8:9], v[118:119], 0, v[8:9]
	v_lshl_add_u32 v113, v84, 1, s29
	global_load_dwordx4 v[50:53], v[8:9], off
	global_load_dwordx4 v[46:49], v[8:9], off offset:64
	global_load_dwordx4 v[38:41], v[8:9], off offset:128
	global_load_dwordx4 v[30:33], v[8:9], off offset:192
	v_add_u32_e32 v8, 0x50, v10
	v_add_u32_e32 v10, v113, v132
	ds_read_b128 v[34:37], v10
	v_add_u32_e32 v161, v113, v133
	v_ashrrev_i32_e32 v9, 31, v8
	ds_read_b128 v[78:81], v161 offset:9216
	ds_read_b128 v[162:165], v10 offset:64
	v_lshlrev_b64 v[8:9], 10, v[8:9]
	v_lshl_add_u64 v[8:9], v[118:119], 0, v[8:9]
	global_load_dwordx4 v[26:29], v[8:9], off
	global_load_dwordx4 v[20:23], v[8:9], off offset:64
	global_load_dwordx4 v[12:15], v[8:9], off offset:128
	s_nop 0
	global_load_dwordx4 v[8:11], v[8:9], off offset:192
	ds_read_b128 v[168:171], v161 offset:9280
	s_waitcnt lgkmcnt(2)
	v_mfma_f32_16x16x32_bf16 v[78:81], v[78:81], v[34:37], 0
	v_add3_u32 v161, s29, v134, v90
	ds_read_b128 v[172:175], v161 offset:13824
	global_load_dwordx4 v[34:37], v[126:127], off
	s_waitcnt lgkmcnt(1)
	v_mfma_f32_16x16x32_bf16 v[78:81], v[168:171], v[162:165], v[78:81]
	ds_read_b128 v[162:165], v161 offset:13888
	v_add_u32_e32 v168, s15, v107
	v_ashrrev_i32_e32 v169, 31, v168
	s_waitcnt lgkmcnt(1)
	v_mfma_f32_16x16x32_bf16 v[66:69], v[172:175], v[66:69], v[78:81]
	v_add_u32_e32 v212, s15, v24
	v_ashrrev_i32_e32 v213, 31, v212
	s_xor_b32 s16, s19, 1
	v_lshlrev_b64 v[78:79], 10, v[168:169]
	ds_read_b128 v[168:171], v161 offset:13952
	s_waitcnt lgkmcnt(1)
	v_mfma_f32_16x16x32_bf16 v[66:69], v[162:165], v[62:65], v[66:69]
	v_lshl_add_u64 v[172:173], v[120:121], 0, v[78:79]
	global_load_dwordx4 v[62:65], v[172:173], off offset:192
	global_load_dwordx4 v[78:81], v[172:173], off offset:128
	ds_read_b128 v[162:165], v161 offset:14016
	s_waitcnt lgkmcnt(1)
	v_mfma_f32_16x16x32_bf16 v[168:171], v[168:171], v[58:61], v[66:69]
	global_load_dwordx4 v[58:61], v[172:173], off offset:64
	s_nop 1
	global_load_dwordx4 v[66:69], v[172:173], off
	s_mul_i32 s16, s16, 0xa000
	s_add_i32 s15, s15, 64
	s_waitcnt lgkmcnt(0)
	v_mfma_f32_16x16x32_bf16 v[54:57], v[162:165], v[54:57], v[168:171]
	v_and_b32_e32 v164, 15, v187
	v_lshrrev_b32_e32 v165, 4, v187
	v_lshlrev_b32_e32 v161, 2, v165
	v_sub_u32_e32 v161, v164, v161
	v_add_u32_e32 v212, v212, v161
	v_ashrrev_i32_e32 v213, 31, v212
	v_lshlrev_b64 v[162:163], 11, v[212:213]
	v_lshl_add_u64 v[162:163], v[116:117], 0, v[162:163]
	v_lshlrev_b32_e32 v165, 3, v165
	v_lshlrev_b32_e32 v164, 1, v164
	v_sub_u32_e32 v164, v165, v164
	v_ashrrev_i32_e32 v165, 31, v164
	v_lshl_add_u64 v[162:163], v[162:163], 0, v[164:165]
	s_add_i32 s18, s18, 1
	s_cmpk_eq_i32 s15, 0x7c0
	s_nop 3
	v_cvt_pk_bf16_f32 v54, v54, v55
	v_cvt_pk_bf16_f32 v55, v56, v57
	global_store_dwordx2 v[162:163], v[54:55], off
	s_nop 0
	s_nop 0
	s_nop 0
	s_nop 0
	s_nop 0
	s_nop 0
	v_add_u32_e32 v161, v113, v135
	ds_read_b128 v[162:165], v161 offset:22528
	v_add_u32_e32 v113, v113, v142
	ds_read_b128 v[168:171], v113 offset:9216
	ds_read_b128 v[172:175], v113 offset:11520
	ds_read_b128 v[176:179], v161 offset:22592
	ds_read_b128 v[180:183], v113 offset:9280
	s_waitcnt lgkmcnt(3)
	v_mfma_f32_16x16x32_bf16 v[0:3], v[162:165], v[168:171], v[0:3]
	ds_read_b128 v[168:171], v113 offset:11584
	s_nop 0
	s_nop 0
	s_waitcnt lgkmcnt(3)
	v_mfma_f32_16x16x32_bf16 v[4:7], v[162:165], v[172:175], v[4:7]
	s_nop 0
	s_nop 0
	s_nop 0
	s_waitcnt lgkmcnt(1)
	v_mfma_f32_16x16x32_bf16 v[0:3], v[176:179], v[180:183], v[0:3]
	s_nop 0
	s_nop 0
	s_nop 0
	s_waitcnt lgkmcnt(0)
	v_mfma_f32_16x16x32_bf16 v[4:7], v[176:179], v[168:171], v[4:7]
	s_nop 0
	s_waitcnt vmcnt(16)
	s_nop 0
	v_pk_mul_f32 v[2:3], v[44:45], v[2:3]
	v_pk_mul_f32 v[0:1], v[42:43], v[0:1]
	s_nop 0
	s_nop 0
	s_nop 0
	v_pk_mul_f32 v[6:7], v[44:45], v[6:7]
	v_pk_mul_f32 v[4:5], v[42:43], v[4:5]
	v_cvt_pk_bf16_f32 v42, v0, v1
	v_cvt_pk_bf16_f32 v43, v2, v3
	v_add3_u32 v44, v146, s16, v143
	s_mov_b64 s[16:17], 0x800
	ds_write_b64 v44, v[42:43] offset:13824
	v_cvt_pk_bf16_f32 v42, v4, v5
	v_cvt_pk_bf16_f32 v43, v6, v7
	v_lshl_add_u64 v[126:127], v[126:127], 0, s[16:17]
	s_nop 0
	ds_write_b64 v44, v[42:43] offset:18176
	s_cbranch_scc1 .LBB0_1092
	s_waitcnt vmcnt(5)
	v_mov_b64_e32 v[44:45], v[36:37]
	s_waitcnt vmcnt(4)
	v_mov_b64_e32 v[54:55], v[62:63]
	v_mov_b64_e32 v[42:43], v[34:35]
	v_mov_b64_e32 v[56:57], v[64:65]
	s_waitcnt vmcnt(2)
	v_mov_b32_e32 v62, v58
	v_mov_b32_e32 v63, v59
	v_mov_b32_e32 v64, v60
	v_mov_b32_e32 v65, v61
	v_mov_b32_e32 v58, v78
	v_mov_b32_e32 v59, v79
	v_mov_b32_e32 v60, v80
	v_mov_b32_e32 v61, v81
	s_branch .LBB0_1086
